# e35: e33 + grid-barrier followers keep four staggered device-scope polls of the XCD generation word in flight instead of one
# baseline (speedup 1.0000x reference)
; __device__ __forceinline__ unsigned xb_ld(unsigned* p)              { return __hip_atomic_load(p, __ATOMIC_RELAXED, __HIP_MEMORY_SCOPE_AGENT); }
; __device__ __forceinline__ unsigned xb_add(unsigned* p, unsigned v) { return __hip_atomic_fetch_add(p, v, __ATOMIC_RELAXED, __HIP_MEMORY_SCOPE_AGENT); }
; #define XB_SPIN(cond, bar) do { unsigned _sp = 0; while (cond) { __builtin_amdgcn_s_sleep(1); \
;     if ((++_sp & 255u) == 0u) { if (xb_ld(&(bar)[XB_TMO])) break; if (_sp > XB_SPIN_CAP) { atomicAdd(&(bar)[XB_TMO], 1u); break; } } } } while (0)
; __device__ __forceinline__ void xcd_barrier(const XcdBarrier& b) {
;     ...
;         const unsigned old = xb_add(&bar[XB_XSUB(b.x)], 1u);
;         const unsigned gen = old / nloc;
;         if (old + 1u == (gen + 1u) * nloc) {
;             __builtin_amdgcn_fence(__ATOMIC_RELEASE, "agent");
;             asm volatile("s_waitcnt vmcnt(0)" ::: "memory");
;             const unsigned og = xb_add(&bar[XB_TOP], 1u);
;             const unsigned tg = og / nx;
;             if (og + 1u == (tg + 1u) * nx) xb_add(&bar[XB_TOPGEN], 1u);
;             else XB_SPIN(xb_ld(&bar[XB_TOPGEN]) == tg, bar);
;             __builtin_amdgcn_fence(__ATOMIC_ACQUIRE, "agent");
;             xb_add(&bar[XB_XGEN(b.x)], 1u);
;             asm volatile("s_waitcnt vmcnt(0)" ::: "memory");
;         } else {
;             XB_SPIN(xb_ld(&bar[XB_XGEN(b.x)]) == gen, bar);
;             __builtin_amdgcn_fence(__ATOMIC_ACQUIRE, "agent");
;             asm volatile("s_waitcnt vmcnt(0)" ::: "memory");
;         }
;     }
;     __syncthreads();
.LBB0_97:
	s_or_b64 exec, exec, s[10:11]
	v_cvt_f32_u32_e32 v5, v3
	s_waitcnt vmcnt(0)
	v_readfirstlane_b32 s0, v4
	v_sub_u32_e32 v4, 0, v3
	v_rcp_iflag_f32_e32 v5, v5
	v_add_u32_e32 v6, s0, v2
	v_mul_f32_e32 v5, 0x4f7ffffe, v5
	v_cvt_u32_f32_e32 v5, v5
	v_mul_lo_u32 v2, v4, v5
	v_mul_hi_u32 v2, v5, v2
	v_add_u32_e32 v2, v5, v2
	v_mul_hi_u32 v2, v6, v2
	v_mul_lo_u32 v4, v2, v3
	v_sub_u32_e32 v4, v6, v4
	v_add_u32_e32 v5, 1, v2
	v_cmp_ge_u32_e32 vcc, v4, v3
	s_nop 1
	v_cndmask_b32_e32 v2, v2, v5, vcc
	v_sub_u32_e32 v5, v4, v3
	v_cndmask_b32_e32 v4, v4, v5, vcc
	v_add_u32_e32 v5, 1, v2
	v_cmp_ge_u32_e32 vcc, v4, v3
	v_add_u32_e32 v4, 1, v6
	s_nop 0
	v_cndmask_b32_e32 v2, v2, v5, vcc
	v_mul_lo_u32 v5, v3, v2
	v_add_u32_e32 v3, v5, v3
	v_cmp_ne_u32_e32 vcc, v4, v3
	s_and_saveexec_b64 s[0:1], vcc
	s_xor_b64 s[8:9], exec, s[0:1]
	s_cbranch_execz .LBB0_111
	s_waitcnt lgkmcnt(0)
	buffer_inv sc1
	v_mov_b32_e32 v1, 0x2000
	global_load_dword v1, v1, s[6:7] offset:1024 sc1
	s_add_u32 s12, s6, 0x2400
	s_addc_u32 s13, s7, 0
	s_waitcnt vmcnt(0)
	v_cmp_eq_u32_e32 vcc, v1, v2
	s_and_saveexec_b64 s[10:11], vcc
	s_cbranch_execz .LBB0_110
	v_mov_b32_e32 v1, 0
	v_readfirstlane_b32 s0, v2
	s_mov_b32 s14, 0
	global_load_dword v3, v1, s[12:13] sc1
	s_sleep 6
	global_load_dword v4, v1, s[12:13] sc1
	s_sleep 6
	global_load_dword v5, v1, s[12:13] sc1
	s_sleep 6
	global_load_dword v6, v1, s[12:13] sc1
.Lbp0:
	s_waitcnt vmcnt(3)
	v_readfirstlane_b32 s1, v3
	s_cmp_lg_u32 s1, s0
	s_cbranch_scc1 .Lbp0_done
	global_load_dword v3, v1, s[12:13] sc1
	s_sleep 6
	s_waitcnt vmcnt(3)
	v_readfirstlane_b32 s1, v4
	s_cmp_lg_u32 s1, s0
	s_cbranch_scc1 .Lbp0_done
	global_load_dword v4, v1, s[12:13] sc1
	s_sleep 6
	s_waitcnt vmcnt(3)
	v_readfirstlane_b32 s1, v5
	s_cmp_lg_u32 s1, s0
	s_cbranch_scc1 .Lbp0_done
	global_load_dword v5, v1, s[12:13] sc1
	s_sleep 6
	s_waitcnt vmcnt(3)
	v_readfirstlane_b32 s1, v6
	s_cmp_lg_u32 s1, s0
	s_cbranch_scc1 .Lbp0_done
	global_load_dword v6, v1, s[12:13] sc1
	s_sleep 6
	s_add_u32 s14, s14, 1
	s_cmp_lt_u32 s14, 0x40000
	s_cbranch_scc1 .Lbp0
.Lbp0_done:
.LBB0_110:
	s_or_b64 exec, exec, s[10:11]
	s_waitcnt vmcnt(0)
	s_waitcnt vmcnt(0)

; __device__ __forceinline__ unsigned xb_ld(unsigned* p)              { return __hip_atomic_load(p, __ATOMIC_RELAXED, __HIP_MEMORY_SCOPE_AGENT); }
; __device__ __forceinline__ unsigned xb_add(unsigned* p, unsigned v) { return __hip_atomic_fetch_add(p, v, __ATOMIC_RELAXED, __HIP_MEMORY_SCOPE_AGENT); }
; #define XB_SPIN(cond, bar) do { unsigned _sp = 0; while (cond) { __builtin_amdgcn_s_sleep(1); \
;     if ((++_sp & 255u) == 0u) { if (xb_ld(&(bar)[XB_TMO])) break; if (_sp > XB_SPIN_CAP) { atomicAdd(&(bar)[XB_TMO], 1u); break; } } } } while (0)
; __device__ __forceinline__ void xcd_barrier(const XcdBarrier& b) {
;     ...
;         const unsigned old = xb_add(&bar[XB_XSUB(b.x)], 1u);
;         const unsigned gen = old / nloc;
;         if (old + 1u == (gen + 1u) * nloc) {
;             __builtin_amdgcn_fence(__ATOMIC_RELEASE, "agent");
;             asm volatile("s_waitcnt vmcnt(0)" ::: "memory");
;             const unsigned og = xb_add(&bar[XB_TOP], 1u);
;             const unsigned tg = og / nx;
;             if (og + 1u == (tg + 1u) * nx) xb_add(&bar[XB_TOPGEN], 1u);
;             else XB_SPIN(xb_ld(&bar[XB_TOPGEN]) == tg, bar);
;             __builtin_amdgcn_fence(__ATOMIC_ACQUIRE, "agent");
;             xb_add(&bar[XB_XGEN(b.x)], 1u);
;             asm volatile("s_waitcnt vmcnt(0)" ::: "memory");
;         } else {
;             XB_SPIN(xb_ld(&bar[XB_XGEN(b.x)]) == gen, bar);
;             __builtin_amdgcn_fence(__ATOMIC_ACQUIRE, "agent");
;             asm volatile("s_waitcnt vmcnt(0)" ::: "memory");
;         }
;     }
;     __syncthreads();
.LBB0_1016:
	s_or_b64 exec, exec, s[8:9]
	v_cvt_f32_u32_e32 v5, v3
	s_waitcnt vmcnt(0)
	v_readfirstlane_b32 s0, v4
	v_sub_u32_e32 v4, 0, v3
	v_rcp_iflag_f32_e32 v5, v5
	v_add_u32_e32 v6, s0, v2
	v_mul_f32_e32 v5, 0x4f7ffffe, v5
	v_cvt_u32_f32_e32 v5, v5
	v_mul_lo_u32 v2, v4, v5
	v_mul_hi_u32 v2, v5, v2
	v_add_u32_e32 v2, v5, v2
	v_mul_hi_u32 v2, v6, v2
	v_mul_lo_u32 v4, v2, v3
	v_sub_u32_e32 v4, v6, v4
	v_add_u32_e32 v5, 1, v2
	v_cmp_ge_u32_e32 vcc, v4, v3
	s_nop 1
	v_cndmask_b32_e32 v2, v2, v5, vcc
	v_sub_u32_e32 v5, v4, v3
	v_cndmask_b32_e32 v4, v4, v5, vcc
	v_add_u32_e32 v5, 1, v2
	v_cmp_ge_u32_e32 vcc, v4, v3
	v_add_u32_e32 v4, 1, v6
	s_nop 0
	v_cndmask_b32_e32 v2, v2, v5, vcc
	v_mul_lo_u32 v5, v3, v2
	v_add_u32_e32 v3, v5, v3
	v_cmp_ne_u32_e32 vcc, v4, v3
	s_and_saveexec_b64 s[0:1], vcc
	s_xor_b64 s[6:7], exec, s[0:1]
	s_cbranch_execz .LBB0_1030
	s_waitcnt lgkmcnt(0)
	buffer_inv sc1
	v_mov_b32_e32 v1, 0x2000
	global_load_dword v1, v1, s[4:5] offset:1024 sc1
	s_add_u32 s10, s4, 0x2400
	s_addc_u32 s11, s5, 0
	s_waitcnt vmcnt(0)
	v_cmp_eq_u32_e32 vcc, v1, v2
	s_and_saveexec_b64 s[8:9], vcc
	s_cbranch_execz .LBB0_1029
	v_mov_b32_e32 v1, 0
	v_readfirstlane_b32 s0, v2
	s_mov_b32 s14, 0
	global_load_dword v3, v1, s[10:11] sc1
	s_sleep 6
	global_load_dword v4, v1, s[10:11] sc1
	s_sleep 6
	global_load_dword v5, v1, s[10:11] sc1
	s_sleep 6
	global_load_dword v6, v1, s[10:11] sc1
.Lbp3:
	s_waitcnt vmcnt(3)
	v_readfirstlane_b32 s1, v3
	s_cmp_lg_u32 s1, s0
	s_cbranch_scc1 .Lbp3_done
	global_load_dword v3, v1, s[10:11] sc1
	s_sleep 6
	s_waitcnt vmcnt(3)
	v_readfirstlane_b32 s1, v4
	s_cmp_lg_u32 s1, s0
	s_cbranch_scc1 .Lbp3_done
	global_load_dword v4, v1, s[10:11] sc1
	s_sleep 6
	s_waitcnt vmcnt(3)
	v_readfirstlane_b32 s1, v5
	s_cmp_lg_u32 s1, s0
	s_cbranch_scc1 .Lbp3_done
	global_load_dword v5, v1, s[10:11] sc1
	s_sleep 6
	s_waitcnt vmcnt(3)
	v_readfirstlane_b32 s1, v6
	s_cmp_lg_u32 s1, s0
	s_cbranch_scc1 .Lbp3_done
	global_load_dword v6, v1, s[10:11] sc1
	s_sleep 6
	s_add_u32 s14, s14, 1
	s_cmp_lt_u32 s14, 0x40000
	s_cbranch_scc1 .Lbp3
.Lbp3_done:
.LBB0_1029:
	s_or_b64 exec, exec, s[8:9]
	s_waitcnt vmcnt(0)
	s_waitcnt vmcnt(0)
